# Hyena small item: 3-tap conv loads batched (48 loads, one wait, edges selected afterwards) and gate edge loads no longer waited individually
# speedup vs baseline: 1.0180x; 1.0045x over previous
.LBB0_114:
	v_add_u32_e32 v7, 0x100, v7
	s_movk_i32 s20, 0x5df
	v_cmp_lt_u32_e64 s[42:43], s20, v7
	ds_write_b128 v6, v[210:213]
	s_or_b64 s[0:1], s[42:43], s[0:1]
	v_add_u32_e32 v6, 0x1000, v6
	s_andn2_b64 exec, exec, s[0:1]
	s_cbranch_execnz .LBB0_114
	s_or_b64 exec, exec, s[0:1]
	s_add_i32 s30, s26, 0x400
	s_lshl_b64 s[20:21], s[30:31], 2
	s_add_u32 s0, s89, s20
	s_addc_u32 s1, s90, s21
	s_waitcnt lgkmcnt(0)
	s_barrier
	global_load_dword v15, v1, s[0:1]
	s_lshl_b64 s[0:1], s[28:29], 2
	s_add_u32 s22, s89, s0
	s_addc_u32 s23, s90, s1
	s_add_u32 s20, s91, s20
	v_mov_b32_e32 v6, 0x5000
	v_mov_b32_e32 v7, 0x8000
	s_addc_u32 s21, s92, s21
	global_load_dword v6, v6, s[22:23]
	s_movk_i32 s4, 0xff
	global_load_dword v7, v7, s[22:23]
	v_cmp_ne_u32_e64 s[42:43], s4, v3
	global_load_dword v16, v1, s[20:21]
	v_readlane_b32 s4, v254, 23
	s_lshl_b64 s[20:21], s[30:31], 14
	v_readlane_b32 s6, v254, 25
	s_waitcnt vmcnt(6)
	v_lshrrev_b32_e32 v8, 5, v3
	s_waitcnt vmcnt(21)
	v_and_b32_e32 v9, 31, v14
	v_readlane_b32 s7, v254, 26
	s_add_u32 s20, s6, s20
	v_mul_u32_u24_e32 v8, 0x50, v8
	v_lshlrev_b32_e32 v9, 1, v9
	s_addc_u32 s21, s7, s21
	s_waitcnt vmcnt(15)
	v_add3_u32 v17, v8, v9, s54
	v_lshl_add_u64 v[8:9], s[20:21], 0, v[0:1]
	s_mov_b64 s[20:21], 0
	v_readlane_b32 s5, v254, 24
	s_mov_b64 s[22:23], 0x1000
	v_lshl_add_u64 v[244:245], v[8:9], 0, s[22:23]
	global_load_ushort v128, v[8:9], off offset:-2
	global_load_ushort v129, v[8:9], off
	global_load_ushort v130, v[8:9], off offset:2
	global_load_ushort v131, v[8:9], off offset:510
	global_load_ushort v132, v[8:9], off offset:512
	global_load_ushort v133, v[8:9], off offset:514
	global_load_ushort v134, v[8:9], off offset:1022
	global_load_ushort v135, v[8:9], off offset:1024
	global_load_ushort v136, v[8:9], off offset:1026
	global_load_ushort v137, v[8:9], off offset:1534
	global_load_ushort v138, v[8:9], off offset:1536
	global_load_ushort v139, v[8:9], off offset:1538
	global_load_ushort v140, v[8:9], off offset:2046
	global_load_ushort v141, v[8:9], off offset:2048
	global_load_ushort v142, v[8:9], off offset:2050
	global_load_ushort v143, v[8:9], off offset:2558
	global_load_ushort v144, v[8:9], off offset:2560
	global_load_ushort v145, v[8:9], off offset:2562
	global_load_ushort v146, v[8:9], off offset:3070
	global_load_ushort v147, v[8:9], off offset:3072
	global_load_ushort v148, v[8:9], off offset:3074
	global_load_ushort v149, v[8:9], off offset:3582
	global_load_ushort v150, v[8:9], off offset:3584
	global_load_ushort v151, v[8:9], off offset:3586
	global_load_ushort v152, v[244:245], off offset:-2
	global_load_ushort v153, v[244:245], off
	global_load_ushort v154, v[244:245], off offset:2
	global_load_ushort v155, v[244:245], off offset:510
	global_load_ushort v156, v[244:245], off offset:512
	global_load_ushort v157, v[244:245], off offset:514
	global_load_ushort v158, v[244:245], off offset:1022
	global_load_ushort v159, v[244:245], off offset:1024
	global_load_ushort v160, v[244:245], off offset:1026
	global_load_ushort v161, v[244:245], off offset:1534
	global_load_ushort v162, v[244:245], off offset:1536
	global_load_ushort v163, v[244:245], off offset:1538
	global_load_ushort v164, v[244:245], off offset:2046
	global_load_ushort v165, v[244:245], off offset:2048
	global_load_ushort v166, v[244:245], off offset:2050
	global_load_ushort v167, v[244:245], off offset:2558
	global_load_ushort v168, v[244:245], off offset:2560
	global_load_ushort v169, v[244:245], off offset:2562
	global_load_ushort v170, v[244:245], off offset:3070
	global_load_ushort v171, v[244:245], off offset:3072
	global_load_ushort v172, v[244:245], off offset:3074
	global_load_ushort v173, v[244:245], off offset:3582
	global_load_ushort v174, v[244:245], off offset:3584
	global_load_ushort v175, v[244:245], off offset:3586
	s_waitcnt vmcnt(0)
	v_lshlrev_b32_e32 v0, 16, v128
	v_lshlrev_b32_e32 v12, 16, v129
	v_lshlrev_b32_e32 v13, 16, v130
	v_cndmask_b32_e64 v0, 0, v0, s[40:41]
	v_cndmask_b32_e64 v13, 0, v13, s[42:43]
	v_pk_mul_f32 v[12:13], v[6:7], v[12:13]
	s_nop 0
	v_fma_f32 v0, v15, v0, v12
	v_add_f32_e32 v0, v0, v13
	v_add_f32_e32 v0, v16, v0
	v_cvt_pk_bf16_f32 v0, v0, s0
	ds_write_b16 v17, v0
	v_lshlrev_b32_e32 v0, 16, v131
	v_lshlrev_b32_e32 v12, 16, v132
	v_lshlrev_b32_e32 v13, 16, v133
	v_cndmask_b32_e64 v0, 0, v0, s[40:41]
	v_cndmask_b32_e64 v13, 0, v13, s[42:43]
	v_pk_mul_f32 v[12:13], v[6:7], v[12:13]
	s_nop 0
	v_fma_f32 v0, v15, v0, v12
	v_add_f32_e32 v0, v0, v13
	v_add_f32_e32 v0, v16, v0
	v_cvt_pk_bf16_f32 v0, v0, s0
	ds_write_b16 v17, v0 offset:1760
	v_lshlrev_b32_e32 v0, 16, v134
	v_lshlrev_b32_e32 v12, 16, v135
	v_lshlrev_b32_e32 v13, 16, v136
	v_cndmask_b32_e64 v0, 0, v0, s[40:41]
	v_cndmask_b32_e64 v13, 0, v13, s[42:43]
	v_pk_mul_f32 v[12:13], v[6:7], v[12:13]
	s_nop 0
	v_fma_f32 v0, v15, v0, v12
	v_add_f32_e32 v0, v0, v13
	v_add_f32_e32 v0, v16, v0
	v_cvt_pk_bf16_f32 v0, v0, s0
	ds_write_b16 v17, v0 offset:3520
	v_lshlrev_b32_e32 v0, 16, v137
	v_lshlrev_b32_e32 v12, 16, v138
	v_lshlrev_b32_e32 v13, 16, v139
	v_cndmask_b32_e64 v0, 0, v0, s[40:41]
	v_cndmask_b32_e64 v13, 0, v13, s[42:43]
	v_pk_mul_f32 v[12:13], v[6:7], v[12:13]
	s_nop 0
	v_fma_f32 v0, v15, v0, v12
	v_add_f32_e32 v0, v0, v13
	v_add_f32_e32 v0, v16, v0
	v_cvt_pk_bf16_f32 v0, v0, s0
	ds_write_b16 v17, v0 offset:5280
	v_add_u32_e32 v17, 0x1b80, v17
	v_lshlrev_b32_e32 v0, 16, v140
	v_lshlrev_b32_e32 v12, 16, v141
	v_lshlrev_b32_e32 v13, 16, v142
	v_cndmask_b32_e64 v0, 0, v0, s[40:41]
	v_cndmask_b32_e64 v13, 0, v13, s[42:43]
	v_pk_mul_f32 v[12:13], v[6:7], v[12:13]
	s_nop 0
	v_fma_f32 v0, v15, v0, v12
	v_add_f32_e32 v0, v0, v13
	v_add_f32_e32 v0, v16, v0
	v_cvt_pk_bf16_f32 v0, v0, s0
	ds_write_b16 v17, v0
	v_lshlrev_b32_e32 v0, 16, v143
	v_lshlrev_b32_e32 v12, 16, v144
	v_lshlrev_b32_e32 v13, 16, v145
	v_cndmask_b32_e64 v0, 0, v0, s[40:41]
	v_cndmask_b32_e64 v13, 0, v13, s[42:43]
	v_pk_mul_f32 v[12:13], v[6:7], v[12:13]
	s_nop 0
	v_fma_f32 v0, v15, v0, v12
	v_add_f32_e32 v0, v0, v13
	v_add_f32_e32 v0, v16, v0
	v_cvt_pk_bf16_f32 v0, v0, s0
	ds_write_b16 v17, v0 offset:1760
	v_lshlrev_b32_e32 v0, 16, v146
	v_lshlrev_b32_e32 v12, 16, v147
	v_lshlrev_b32_e32 v13, 16, v148
	v_cndmask_b32_e64 v0, 0, v0, s[40:41]
	v_cndmask_b32_e64 v13, 0, v13, s[42:43]
	v_pk_mul_f32 v[12:13], v[6:7], v[12:13]
	s_nop 0
	v_fma_f32 v0, v15, v0, v12
	v_add_f32_e32 v0, v0, v13
	v_add_f32_e32 v0, v16, v0
	v_cvt_pk_bf16_f32 v0, v0, s0
	ds_write_b16 v17, v0 offset:3520
	v_lshlrev_b32_e32 v0, 16, v149
	v_lshlrev_b32_e32 v12, 16, v150
	v_lshlrev_b32_e32 v13, 16, v151
	v_cndmask_b32_e64 v0, 0, v0, s[40:41]
	v_cndmask_b32_e64 v13, 0, v13, s[42:43]
	v_pk_mul_f32 v[12:13], v[6:7], v[12:13]
	s_nop 0
	v_fma_f32 v0, v15, v0, v12
	v_add_f32_e32 v0, v0, v13
	v_add_f32_e32 v0, v16, v0
	v_cvt_pk_bf16_f32 v0, v0, s0
	ds_write_b16 v17, v0 offset:5280
	v_add_u32_e32 v17, 0x1b80, v17
	v_lshlrev_b32_e32 v0, 16, v152
	v_lshlrev_b32_e32 v12, 16, v153
	v_lshlrev_b32_e32 v13, 16, v154
	v_cndmask_b32_e64 v0, 0, v0, s[40:41]
	v_cndmask_b32_e64 v13, 0, v13, s[42:43]
	v_pk_mul_f32 v[12:13], v[6:7], v[12:13]
	s_nop 0
	v_fma_f32 v0, v15, v0, v12
	v_add_f32_e32 v0, v0, v13
	v_add_f32_e32 v0, v16, v0
	v_cvt_pk_bf16_f32 v0, v0, s0
	ds_write_b16 v17, v0
	v_lshlrev_b32_e32 v0, 16, v155
	v_lshlrev_b32_e32 v12, 16, v156
	v_lshlrev_b32_e32 v13, 16, v157
	v_cndmask_b32_e64 v0, 0, v0, s[40:41]
	v_cndmask_b32_e64 v13, 0, v13, s[42:43]
	v_pk_mul_f32 v[12:13], v[6:7], v[12:13]
	s_nop 0
	v_fma_f32 v0, v15, v0, v12
	v_add_f32_e32 v0, v0, v13
	v_add_f32_e32 v0, v16, v0
	v_cvt_pk_bf16_f32 v0, v0, s0
	ds_write_b16 v17, v0 offset:1760
	v_lshlrev_b32_e32 v0, 16, v158
	v_lshlrev_b32_e32 v12, 16, v159
	v_lshlrev_b32_e32 v13, 16, v160
	v_cndmask_b32_e64 v0, 0, v0, s[40:41]
	v_cndmask_b32_e64 v13, 0, v13, s[42:43]
	v_pk_mul_f32 v[12:13], v[6:7], v[12:13]
	s_nop 0
	v_fma_f32 v0, v15, v0, v12
	v_add_f32_e32 v0, v0, v13
	v_add_f32_e32 v0, v16, v0
	v_cvt_pk_bf16_f32 v0, v0, s0
	ds_write_b16 v17, v0 offset:3520
	v_lshlrev_b32_e32 v0, 16, v161
	v_lshlrev_b32_e32 v12, 16, v162
	v_lshlrev_b32_e32 v13, 16, v163
	v_cndmask_b32_e64 v0, 0, v0, s[40:41]
	v_cndmask_b32_e64 v13, 0, v13, s[42:43]
	v_pk_mul_f32 v[12:13], v[6:7], v[12:13]
	s_nop 0
	v_fma_f32 v0, v15, v0, v12
	v_add_f32_e32 v0, v0, v13
	v_add_f32_e32 v0, v16, v0
	v_cvt_pk_bf16_f32 v0, v0, s0
	ds_write_b16 v17, v0 offset:5280
	v_add_u32_e32 v17, 0x1b80, v17
	v_lshlrev_b32_e32 v0, 16, v164
	v_lshlrev_b32_e32 v12, 16, v165
	v_lshlrev_b32_e32 v13, 16, v166
	v_cndmask_b32_e64 v0, 0, v0, s[40:41]
	v_cndmask_b32_e64 v13, 0, v13, s[42:43]
	v_pk_mul_f32 v[12:13], v[6:7], v[12:13]
	s_nop 0
	v_fma_f32 v0, v15, v0, v12
	v_add_f32_e32 v0, v0, v13
	v_add_f32_e32 v0, v16, v0
	v_cvt_pk_bf16_f32 v0, v0, s0
	ds_write_b16 v17, v0
	v_lshlrev_b32_e32 v0, 16, v167
	v_lshlrev_b32_e32 v12, 16, v168
	v_lshlrev_b32_e32 v13, 16, v169
	v_cndmask_b32_e64 v0, 0, v0, s[40:41]
	v_cndmask_b32_e64 v13, 0, v13, s[42:43]
	v_pk_mul_f32 v[12:13], v[6:7], v[12:13]
	s_nop 0
	v_fma_f32 v0, v15, v0, v12
	v_add_f32_e32 v0, v0, v13
	v_add_f32_e32 v0, v16, v0
	v_cvt_pk_bf16_f32 v0, v0, s0
	ds_write_b16 v17, v0 offset:1760
	v_lshlrev_b32_e32 v0, 16, v170
	v_lshlrev_b32_e32 v12, 16, v171
	v_lshlrev_b32_e32 v13, 16, v172
	v_cndmask_b32_e64 v0, 0, v0, s[40:41]
	v_cndmask_b32_e64 v13, 0, v13, s[42:43]
	v_pk_mul_f32 v[12:13], v[6:7], v[12:13]
	s_nop 0
	v_fma_f32 v0, v15, v0, v12
	v_add_f32_e32 v0, v0, v13
	v_add_f32_e32 v0, v16, v0
	v_cvt_pk_bf16_f32 v0, v0, s0
	ds_write_b16 v17, v0 offset:3520
	v_lshlrev_b32_e32 v0, 16, v173
	v_lshlrev_b32_e32 v12, 16, v174
	v_lshlrev_b32_e32 v13, 16, v175
	v_cndmask_b32_e64 v0, 0, v0, s[40:41]
	v_cndmask_b32_e64 v13, 0, v13, s[42:43]
	v_pk_mul_f32 v[12:13], v[6:7], v[12:13]
	s_nop 0
	v_fma_f32 v0, v15, v0, v12
	v_add_f32_e32 v0, v0, v13
	v_add_f32_e32 v0, v16, v0
	v_cvt_pk_bf16_f32 v0, v0, s0
	ds_write_b16 v17, v0 offset:5280
	v_add_u32_e32 v17, 0x1b80, v17

.LBB0_139:
	s_add_i32 s30, s22, s28
	s_lshl_b64 s[22:23], s[30:31], 14
	v_lshl_add_u64 v[2:3], v[44:45], 0, s[22:23]
	v_mov_b32_e32 v83, 0
	v_mov_b32_e32 v115, 0
	s_and_saveexec_b64 s[22:23], s[42:43]
	s_cbranch_execz .LBB0_141
	v_lshl_add_u64 v[4:5], v[42:43], 1, v[2:3]
	global_load_ushort v115, v[4:5], off
.LBB0_141:
	s_or_b64 exec, exec, s[22:23]
	v_lshl_add_u64 v[4:5], v[2:3], 0, v[0:1]
	global_load_dwordx2 v[86:87], v[4:5], off
	global_load_ushort v114, v[4:5], off offset:8
	global_load_dwordx3 v[38:40], v[4:5], off offset:14
	global_load_dwordx3 v[34:36], v[4:5], off offset:30
	global_load_dwordx2 v[84:85], v[4:5], off offset:46
	global_load_ushort v108, v[4:5], off offset:54
	s_and_saveexec_b64 s[22:23], s[44:45]
	s_cbranch_execz .LBB0_143
	v_mov_b32_e32 v83, v1
	v_lshl_add_u64 v[2:3], v[2:3], 0, v[82:83]
	global_load_ushort v83, v[2:3], off

.LBB0_145:
	s_mov_b32 s4, 0xffff
	s_waitcnt vmcnt(10)
	v_lshlrev_b32_e32 v115, 16, v115
	v_bfi_b32 v86, s4, v86, v86
	v_lshlrev_b32_e32 v116, 16, v86
	s_nop 3
	v_add_f32_e32 v2, v2, v18
	s_waitcnt vmcnt(2)
	v_mul_f32_e32 v18, v112, v116
	v_and_b32_e32 v86, 0xffff0000, v86
	v_fmac_f32_e32 v18, v115, v110
	s_waitcnt vmcnt(1)
	v_fmac_f32_e32 v18, v111, v86
	v_fmac_f32_e32 v2, v109, v117
	s_waitcnt vmcnt(0)
	v_lshlrev_b32_e32 v83, 16, v83
	v_add_f32_e32 v18, v113, v18
	v_mul_f32_e32 v2, v18, v2
	v_cvt_pk_bf16_f32 v18, v2, s0
	s_mov_b64 s[20:21], -1
	s_and_b64 vcc, exec, s[0:1]
	s_cbranch_vccz .LBB0_209
	global_store_short v[50:51], v18, off
	s_cbranch_execz .LBB0_210
